# P2 tile deal: even/odd XCDs exchange column-tile groups 0..3 and 24..27 (instead of 0..3 and 16..19)
# speedup vs baseline: 1.0052x; 1.0052x over previous
.LBB0_176:
	s_cmp_lt_i32 s26, 3
	s_cselect_b64 s[6:7], -1, 0
	s_and_b64 s[10:11], s[6:7], s[4:5]
	s_andn2_b64 vcc, exec, s[10:11]
	s_cbranch_vccnz .LBB0_291
	s_cmpk_lt_i32 s2, 0x300
	s_cselect_b64 s[4:5], -1, 0
	s_cmpk_gt_i32 s2, 0x2ff
	s_mov_b64 s[12:13], s[24:25]
	v_readfirstlane_b32 s22, v0
	s_cbranch_scc1 .LBB0_179
	s_ashr_i32 s6, s2, 31
	s_lshr_b32 s6, s6, 29
	s_add_i32 s6, s2, s6
	s_ashr_i32 s7, s6, 3
	s_and_b32 s6, s6, -8
	s_sub_i32 s6, s2, s6
	s_cmp_lt_i32 s6, 0
	s_movk_i32 s8, 0x61
	s_cselect_b32 s8, s8, 0x60
	s_mul_i32 s6, s6, s8
	s_add_i32 s6, s6, s7
	s_mul_hi_i32 s7, s6, 0x2aaaaaab
	s_lshr_b32 s8, s7, 31
	s_ashr_i32 s7, s7, 5
	s_add_i32 s7, s7, s8
	s_lshl_b32 s8, s7, 3
	s_mulk_i32 s7, 0xc0
	s_sub_i32 s7, s6, s7
	s_sext_i32_i16 s6, s7
	s_bfe_u32 s6, s6, 0x3001c
	s_add_i32 s6, s7, s6
	s_sext_i32_i16 s9, s6
	s_and_b32 s6, s6, 0xfff8
	s_sub_i32 s6, s7, s6
	s_sext_i32_i16 s6, s6
	s_add_i32 s6, s8, s6
	s_ashr_i32 s8, s9, 3
	s_add_i32 s9, s8, 4
	s_cmpk_gt_i32 s7, 0x5f
	s_cselect_b32 s62, s9, s8
	s_add_i32 s7, s62, 24
	s_sub_i32 s8, s62, 24
	s_sub_i32 s9, s62, 0
	s_cmp_lt_u32 s9, 4
	s_cselect_b32 s7, s7, s62
	s_sub_i32 s9, s62, 24
	s_cmp_lt_u32 s9, 4
	s_cselect_b32 s62, s8, s7

.LBB0_185:
	s_add_i32 s83, s83, 1
	s_mul_i32 s4, s83, s84
	s_mul_hi_u32 s5, s83, s3
	s_add_i32 s5, s5, s4
	s_mul_i32 s4, s83, s3
	s_add_u32 s58, s4, s2
	s_addc_u32 s59, s5, s85
	v_mov_b64_e32 v[2:3], 0x300
	v_cmp_lt_i64_e64 s[4:5], s[58:59], v[2:3]
	v_mov_b64_e32 v[2:3], 0x2ff
	v_cmp_gt_i64_e32 vcc, s[58:59], v[2:3]
	s_cbranch_vccnz .LBB0_187
	s_ashr_i32 s7, s58, 31
	s_lshr_b32 s7, s7, 29
	s_add_i32 s7, s58, s7
	s_ashr_i32 s54, s7, 3
	s_and_b32 s7, s7, -8
	s_sub_i32 s7, s58, s7
	s_cmp_lt_i32 s7, 0
	s_cselect_b32 s55, s88, 0x60
	s_mul_i32 s7, s7, s55
	s_add_i32 s7, s7, s54
	s_mul_hi_i32 s54, s7, 0x2aaaaaab
	s_lshr_b32 s55, s54, 31
	s_ashr_i32 s54, s54, 5
	s_add_i32 s54, s54, s55
	s_lshl_b32 s55, s54, 3
	s_sub_i32 s56, 32, s55
	s_min_i32 s56, s56, 8
	s_abs_i32 s57, s56
	v_cvt_f32_u32_e32 v2, s57
	s_sub_i32 s59, 0, s57
	s_mulk_i32 s54, 0xc0
	s_sub_i32 s7, s7, s54
	v_rcp_iflag_f32_e32 v2, v2
	s_abs_i32 s54, s7
	s_xor_b32 s58, s7, s56
	s_ashr_i32 s58, s58, 31
	v_mul_f32_e32 v2, 0x4f7ffffe, v2
	v_cvt_u32_f32_e32 v2, v2
	s_nop 0
	v_readfirstlane_b32 s60, v2
	s_mul_i32 s59, s59, s60
	s_mul_hi_u32 s59, s60, s59
	s_add_i32 s60, s60, s59
	s_mul_hi_u32 s59, s54, s60
	s_mul_i32 s60, s59, s57
	s_sub_i32 s54, s54, s60
	s_add_i32 s61, s59, 1
	s_sub_i32 s60, s54, s57
	s_cmp_ge_u32 s54, s57
	s_cselect_b32 s59, s61, s59
	s_cselect_b32 s54, s60, s54
	s_add_i32 s60, s59, 1
	s_cmp_ge_u32 s54, s57
	s_cselect_b32 s54, s60, s59
	s_xor_b32 s54, s54, s58
	s_sub_i32 s57, s54, s58
	s_mul_i32 s54, s57, s56
	s_sub_i32 s7, s7, s54
	s_add_i32 s54, s55, s7
	s_add_i32 s7, s57, 4
	s_cmp_gt_i32 s57, 11
	s_cselect_b32 s56, s7, s57
	s_add_i32 s57, s56, 24
	s_sub_i32 s58, s56, 24
	s_sub_i32 s59, s56, 0
	s_cmp_lt_u32 s59, 4
	s_cselect_b32 s57, s57, s56
	s_sub_i32 s59, s56, 24
	s_cmp_lt_u32 s59, 4
	s_cselect_b32 s56, s58, s57
